# u1 plus: workgroups that ran a scan skip the exhausted attention and mop-up work-queue polls and go straight to the phase barrier
# speedup vs baseline: 1.0123x; 1.0010x over previous
; DI void mamba_scan(CP p, const Ptrs& w, int l, int item, float* sm) {
;     ...
;   auto flush = [&](int c) {
;     {
;       int j = tid >> 4, rr = tid & 15;
;       int ii = pos2i(c * 16 + j, dir);
;       yout[((size_t)b * TPB + ii) * 512 + hd * 64 + pq * 16 + rr] = f2bf(sY[(c & 1) * 256 + j * 16 + rr]);
;     }
;   };
;     ...
;       if (it < 128) { __builtin_amdgcn_s_setprio(3); rwkv_scan(p, w, l, it, sm); __builtin_amdgcn_s_setprio(0); if (DUMMY) break; continue; }
;       if (it < 256) { __builtin_amdgcn_s_setprio(3); mamba_scan(p, w, l, it - 128, sm); __builtin_amdgcn_s_setprio(0); if (DUMMY) break; continue; }
.LBB0_559:
	s_waitcnt vmcnt(6)
	ds_read_b32 v6, v6
	v_lshlrev_b64 v[4:5], 10, v[4:5]
	v_lshl_add_u64 v[4:5], s[2:3], 0, v[4:5]
	v_lshl_add_u64 v[2:3], v[2:3], 1, v[4:5]
	v_lshl_add_u64 v[0:1], v[0:1], 1, v[2:3]
	s_waitcnt lgkmcnt(0)
	v_cvt_pk_bf16_f32 v2, v6, s0
	s_waitcnt vmcnt(0)
	v_lshl_add_u64 v[0:1], v[32:33], 1, v[0:1]
	global_store_short v[0:1], v2, off
	s_setprio 0
	v_writelane_b32 v254, s62, 58
	s_branch .LBB0_716
